# v6 with the static waves-4-7 priority raise widened to the whole prep+main+post span
# speedup vs baseline: 1.0054x; 1.0054x over previous
; __device__ __forceinline__ int tid_() { int t = threadIdx.x; asm volatile("" : "+v"(t)); return t; }
; #define LAS __attribute__((address_space(3)))
; DI void nsa_rope(KA a) {
;     const int tid = tid_();
;     unsigned char* ws = a->ws; bf16* H = (bf16*)(ws + WS_H); const float* ct = (const float*)(ws + WS_COS); const float* st = (const float*)(ws + WS_SIN);
;     const int ustride = gridDim.x * NTHR;
;     for (int u0 = blockIdx.x * NTHR + tid; u0 < T * 48; u0 += 2 * ustride) {
; DI void prep_phase(KA a, const int l, LAS unsigned char* lds) {
;     nsa_rope(a);
.LBB0_297:
	s_or_b64 exec, exec, s[0:1]
	v_readlane_b32 s12, v252, 0
	v_readlane_b32 s13, v252, 1
	s_waitcnt lgkmcnt(0)
	v_mov_b32_e32 v0, v232
	s_barrier
	v_readfirstlane_b32 s100, v232
	s_nop 3
	s_lshr_b32 s100, s100, 8
	s_cmp_eq_u32 s100, 0
	s_cbranch_scc1 .Lprio_wide_skip
	s_setprio 1
.Lprio_wide_skip:
	s_load_dwordx2 s[14:15], s[12:13], 0x120
	s_xor_b64 s[8:9], s[6:7], -1
	v_readlane_b32 s0, v252, 3
	s_waitcnt lgkmcnt(0)
	s_add_u32 s16, s14, 0x8000000
	s_addc_u32 s17, s15, 0
	s_add_u32 s18, s14, 0x100000
	s_addc_u32 s19, s15, 0
	s_add_u32 s20, s14, 0x140000
	v_add_u32_e32 v52, s0, v0
	s_addc_u32 s21, s15, 0
	v_cmp_gt_i32_e32 vcc, s49, v52
	s_and_saveexec_b64 s[2:3], vcc
	s_cbranch_execz .LBB0_320
	v_readlane_b32 s0, v253, 44
	s_mov_b64 s[4:5], 0
	s_nop 0
	v_lshl_add_u32 v49, v0, 3, s0
	s_branch .LBB0_300
